# SSM layer-0 prompt scan loop: hoisted LDS address adds, prefetched skip-term and next-chunk u rows, removed private-LDS drain fences
# baseline (speedup 1.0000x reference)
; #define LAS __attribute__((address_space(3)))
; __device__ __forceinline__ unsigned pk2(float lo, float hi) { const f32x2 v = {lo, hi}; return __builtin_bit_cast(unsigned, __builtin_convertvector(v, bf16x2_t)); }
; template <bool FULL>
; __device__ __forceinline__ void ssm_core(const Args& a, LAS unsigned char* wl, int j, int L, bool samp, int n, int g, int tb, int te, float& hr, float& hi, int lane) {
;     ...
;         for (int k = 0; k < 4; ++k) {
;             bf16x8 afk;
;             { const LAS f32x4* usrc = (const LAS f32x4*)(Us + (16 * k + c) * 16 + 8 * (G4 & 1)); const f32x4 x0 = usrc[0], x1 = usrc[1];
;               u32x4 aw;
; #pragma unroll
;               for (int e2 = 0; e2 < 4; ++e2) { const float u0 = e2 < 2 ? x0[2 * e2] : x1[2 * e2 - 4], u1 = e2 < 2 ? x0[2 * e2 + 1] : x1[2 * e2 - 3];
;                   const unsigned hp = pk2(u0, u1); const unsigned lp = pk2(u0 - __builtin_bit_cast(float, hp << 16), u1 - __builtin_bit_cast(float, hp & 0xffff0000u)); aw[e2] = G4 < 2 ? hp : lp; }
;               afk = __builtin_bit_cast(bf16x8, aw); }
;             f32x4 dd[8];
; #pragma unroll
;             for (int n8 = 0; n8 < 8; ++n8) dd[n8] = mfma_t(afk, Bf[n8], (f32x4){0.f, 0.f, 0.f, 0.f});
; #pragma unroll
;             for (int n8 = 0; n8 < 8; ++n8)
; #pragma unroll
;                 for (int i = 0; i < 4; ++i) BUs[(4 * G4 + i) * SSM_BUS + 16 * n8 + c] = dd[n8][i];
;             asm volatile("s_waitcnt lgkmcnt(0)" ::: "memory");
; #pragma unroll
;             for (int t = 0; t < 16; ++t) { const float br = BUs[t * SSM_BUS + lane], bi = BUs[t * SSM_BUS + 64 + lane];
;                 const float nr = fmaf(ar, hr, fmaf(-ai, hi, br)), ni = fmaf(ar, hi, fmaf(ai, hr, bi)); hr = nr; hi = ni;
;                 if (FULL) { BUs[t * SSM_BUS + lane] = hr; BUs[t * SSM_BUS + 64 + lane] = hi; } }
.LBB0_285:
	s_waitcnt lgkmcnt(0)
	s_mov_b64 s[36:37], 0
	v_mov_b32_e32 v95, v124
	v_mov_b32_e32 v128, v123
	v_add_u32_e32 v184, 32, v122
	v_add_u32_e32 v185, 48, v122
	v_add_u32_e32 v186, 64, v122
	v_add_u32_e32 v187, 0x50, v122
	v_add_u32_e32 v188, 0x60, v122
	v_add_u32_e32 v189, 0x70, v122
	v_add_u32_e32 v190, 0x80, v122
	v_add_u32_e32 v191, 0x90, v122
	v_add_u32_e32 v192, 0xa0, v122
	v_add_u32_e32 v193, 0xb0, v122
	v_add_u32_e32 v194, 0xc0, v122
	v_add_u32_e32 v195, 0xd0, v122
	v_add_u32_e32 v196, 0xe0, v122
	v_add_u32_e32 v197, 0xf0, v122
	ds_read_b128 v[198:201], v95
	ds_read_b128 v[202:205], v95 offset:16
.LBB0_286:
	v_mov_b64_e32 v[148:149], s[10:11]
	v_mov_b64_e32 v[146:147], s[8:9]
	v_mov_b64_e32 v[152:153], s[10:11]
	s_waitcnt lgkmcnt(1)
	v_mov_b64_e32 v[90:91], v[198:199]
	v_mov_b64_e32 v[92:93], v[200:201]
	v_cvt_pk_bf16_f32 v145, v90, v91
	v_cvt_pk_bf16_f32 v176, v92, v93
	s_waitcnt lgkmcnt(0)
	v_mov_b64_e32 v[86:87], v[202:203]
	v_mov_b64_e32 v[88:89], v[204:205]
	v_cvt_pk_bf16_f32 v177, v86, v87
	v_cvt_pk_bf16_f32 v178, v88, v89
	v_lshlrev_b32_e32 v166, 16, v145
	v_and_b32_e32 v167, 0xffff0000, v145
	v_lshlrev_b32_e32 v168, 16, v176
	v_and_b32_e32 v169, 0xffff0000, v176
	v_lshlrev_b32_e32 v170, 16, v177
	v_and_b32_e32 v171, 0xffff0000, v177
	v_lshlrev_b32_e32 v172, 16, v178
	v_and_b32_e32 v173, 0xffff0000, v178
	v_pk_add_f32 v[90:91], v[90:91], v[166:167] neg_lo:[0,1] neg_hi:[0,1]
	v_pk_add_f32 v[92:93], v[92:93], v[168:169] neg_lo:[0,1] neg_hi:[0,1]
	v_pk_add_f32 v[86:87], v[86:87], v[170:171] neg_lo:[0,1] neg_hi:[0,1]
	v_pk_add_f32 v[88:89], v[88:89], v[172:173] neg_lo:[0,1] neg_hi:[0,1]
	v_cvt_pk_bf16_f32 v90, v90, v91
	v_cvt_pk_bf16_f32 v91, v92, v93
	v_cvt_pk_bf16_f32 v92, v86, v87
	v_cvt_pk_bf16_f32 v89, v88, v89
	v_cndmask_b32_e64 v86, v90, v145, s[6:7]
	v_cndmask_b32_e64 v87, v91, v176, s[6:7]
	v_cndmask_b32_e64 v88, v92, v177, s[6:7]
	v_cndmask_b32_e64 v89, v89, v178, s[6:7]
	v_mov_b64_e32 v[150:151], s[8:9]
	s_nop 4
	v_mov_b64_e32 v[156:157], s[10:11]
	v_mfma_f32_16x16x32_bf16 v[90:93], v[86:89], v[2:5], v[146:149]
	s_nop 7
	s_nop 4
	v_mov_b64_e32 v[154:155], s[8:9]
	v_mfma_f32_16x16x32_bf16 v[150:153], v[86:89], v[6:9], v[150:153]
	v_mov_b64_e32 v[160:161], s[10:11]
	s_nop 7
	s_nop 4
	v_mov_b64_e32 v[158:159], s[8:9]
	v_mfma_f32_16x16x32_bf16 v[154:157], v[86:89], v[10:13], v[154:157]
	v_mov_b64_e32 v[164:165], s[10:11]
	s_nop 7
	s_nop 4
	v_mov_b64_e32 v[162:163], s[8:9]
	v_mfma_f32_16x16x32_bf16 v[158:161], v[86:89], v[14:17], v[158:161]
	v_mov_b64_e32 v[148:149], s[10:11]
	s_nop 7
	s_nop 4
	v_mov_b64_e32 v[146:147], s[8:9]
	v_mfma_f32_16x16x32_bf16 v[162:165], v[86:89], v[34:37], v[162:165]
	v_mov_b64_e32 v[168:169], s[10:11]
	s_nop 7
	s_nop 4
	v_mov_b64_e32 v[166:167], s[8:9]
	v_mfma_f32_16x16x32_bf16 v[146:149], v[86:89], v[38:41], v[146:149]
	v_mov_b64_e32 v[172:173], s[10:11]
	s_nop 7
	s_nop 4
	v_mov_b64_e32 v[170:171], s[8:9]
	v_mfma_f32_16x16x32_bf16 v[166:169], v[86:89], v[42:45], v[166:169]
	s_nop 7
	s_nop 4
	v_add_u32_e32 v134, 0x400, v125
	v_mfma_f32_16x16x32_bf16 v[170:173], v[86:89], v[46:49], v[170:173]
	s_nop 7
	ds_write2_b32 v125, v90, v150 offset1:16
	ds_write2_b32 v125, v91, v151 offset0:132 offset1:148
	ds_write2_b32 v134, v92, v152 offset0:8 offset1:24
	ds_write2_b32 v134, v93, v153 offset0:140 offset1:156
	ds_write2_b32 v125, v154, v158 offset0:32 offset1:48
	ds_write2_b32 v125, v155, v159 offset0:164 offset1:180
	ds_write2_b32 v134, v156, v160 offset0:40 offset1:56
	ds_write2_b32 v134, v157, v161 offset0:172 offset1:188
	ds_write2_b32 v125, v162, v146 offset0:64 offset1:80
	ds_write2_b32 v125, v163, v147 offset0:196 offset1:212
	ds_write2_b32 v134, v164, v148 offset0:72 offset1:88
	ds_write2_b32 v134, v165, v149 offset0:204 offset1:220
	ds_write2_b32 v125, v166, v170 offset0:96 offset1:112
	ds_write2_b32 v125, v167, v171 offset0:228 offset1:244
	ds_write2_b32 v134, v168, v172 offset0:104 offset1:120
	ds_write2_b32 v134, v169, v173 offset0:236 offset1:252
	ds_read2st64_b32 v[86:87], v122 offset1:1
	ds_read2_b32 v[88:89], v122 offset0:132 offset1:196
	ds_read2st64_b32 v[90:91], v184 offset0:4 offset1:5
	ds_read2st64_b32 v[92:93], v185 offset0:6 offset1:7
	ds_read2st64_b32 v[146:147], v186 offset0:8 offset1:9
	ds_read2st64_b32 v[148:149], v187 offset0:10 offset1:11
	ds_read2st64_b32 v[150:151], v188 offset0:12 offset1:13
	ds_read2st64_b32 v[152:153], v189 offset0:14 offset1:15
	ds_read2st64_b32 v[154:155], v190 offset0:16 offset1:17
	ds_read2st64_b32 v[156:157], v191 offset0:18 offset1:19
	ds_read2st64_b32 v[158:159], v192 offset0:20 offset1:21
	ds_read2st64_b32 v[160:161], v193 offset0:22 offset1:23
	ds_read2st64_b32 v[162:163], v194 offset0:24 offset1:25
	ds_read2st64_b32 v[164:165], v195 offset0:26 offset1:27
	ds_read2st64_b32 v[166:167], v196 offset0:28 offset1:29
	ds_read2st64_b32 v[168:169], v197 offset0:30 offset1:31
	s_waitcnt lgkmcnt(14)
	v_pk_fma_f32 v[86:87], v[112:113], v[120:121], v[86:87]
	v_mov_b32_e32 v170, v89
	v_mov_b32_e32 v171, v88
	v_pk_fma_f32 v[86:87], v[114:115], v[120:121], v[86:87] op_sel:[0,0,1] op_sel_hi:[1,1,0]
	s_waitcnt lgkmcnt(13)
	v_mov_b32_e32 v88, v91
	v_pk_fma_f32 v[120:121], v[118:119], v[86:87], v[170:171] op_sel:[0,1,0] op_sel_hi:[1,0,1]
	v_mov_b32_e32 v89, v90
	ds_write2st64_b32 v122, v87, v86 offset1:1
	v_pk_fma_f32 v[86:87], v[114:115], v[86:87], v[120:121]
	s_waitcnt lgkmcnt(13)
	v_mov_b32_e32 v90, v93
	v_pk_fma_f32 v[88:89], v[118:119], v[86:87], v[88:89] op_sel:[0,1,0] op_sel_hi:[1,0,1]
	v_mov_b32_e32 v91, v92
	ds_write2_b32 v122, v87, v86 offset0:132 offset1:196
	v_pk_fma_f32 v[86:87], v[114:115], v[86:87], v[88:89]
	s_waitcnt lgkmcnt(13)
; #define LAS __attribute__((address_space(3)))
; template <bool FULL>
; __device__ __forceinline__ void ssm_core(const Args& a, LAS unsigned char* wl, int j, int L, bool samp, int n, int g, int tb, int te, float& hr, float& hi, int lane) {
;     ...
;             for (int t = 0; t < 16; ++t) { const float br = BUs[t * SSM_BUS + lane], bi = BUs[t * SSM_BUS + 64 + lane];
;                 const float nr = fmaf(ar, hr, fmaf(-ai, hi, br)), ni = fmaf(ar, hi, fmaf(ai, hr, bi)); hr = nr; hi = ni;
;                 if (FULL) { BUs[t * SSM_BUS + lane] = hr; BUs[t * SSM_BUS + 64 + lane] = hi; } }
;             asm volatile("s_waitcnt lgkmcnt(0)" ::: "memory");
;             if (FULL) {
;                 f32x4 y = (f32x4){0.f, 0.f, 0.f, 0.f};
;                 u32x4 hw[4];
; #pragma unroll
;                 for (int kk = 0; kk < 4; ++kk) { const LAS f32x4* hp = (const LAS f32x4*)(BUs + c * SSM_BUS + 32 * kk + 8 * G4); const f32x4 h0 = hp[0], h1 = hp[1];
	v_mov_b32_e32 v92, v147
	v_pk_fma_f32 v[88:89], v[118:119], v[86:87], v[90:91] op_sel:[0,1,0] op_sel_hi:[1,0,1]
	v_mov_b32_e32 v93, v146
	ds_write2st64_b32 v184, v87, v86 offset0:4 offset1:5
	v_pk_fma_f32 v[86:87], v[114:115], v[86:87], v[88:89]
	ds_write2st64_b32 v185, v87, v86 offset0:6 offset1:7
	v_pk_fma_f32 v[88:89], v[118:119], v[86:87], v[92:93] op_sel:[0,1,0] op_sel_hi:[1,0,1]
	s_waitcnt lgkmcnt(12)
	v_mov_b32_e32 v146, v153
	v_pk_fma_f32 v[86:87], v[114:115], v[86:87], v[88:89]
	ds_write2st64_b32 v186, v87, v86 offset0:8 offset1:9
	v_pk_fma_f32 v[88:89], v[112:113], v[86:87], v[148:149]
	v_mov_b32_e32 v147, v152
	v_pk_fma_f32 v[86:87], v[114:115], v[86:87], v[88:89] op_sel:[0,0,1] op_sel_hi:[1,1,0]
	ds_write2st64_b32 v187, v87, v86 offset0:10 offset1:11
	v_pk_fma_f32 v[88:89], v[112:113], v[86:87], v[150:151]
	s_waitcnt lgkmcnt(13)
	v_mov_b32_e32 v152, v155
	v_pk_fma_f32 v[86:87], v[114:115], v[86:87], v[88:89] op_sel:[0,0,1] op_sel_hi:[1,1,0]
	v_mov_b32_e32 v153, v154
	v_pk_fma_f32 v[88:89], v[118:119], v[86:87], v[146:147] op_sel:[0,1,0] op_sel_hi:[1,0,1]
	ds_write2st64_b32 v188, v87, v86 offset0:12 offset1:13
	v_pk_fma_f32 v[86:87], v[114:115], v[86:87], v[88:89]
	s_waitcnt lgkmcnt(13)
	v_mov_b32_e32 v154, v157
	v_pk_fma_f32 v[88:89], v[118:119], v[86:87], v[152:153] op_sel:[0,1,0] op_sel_hi:[1,0,1]
	v_mov_b32_e32 v155, v156
	ds_write2st64_b32 v189, v87, v86 offset0:14 offset1:15
	v_pk_fma_f32 v[86:87], v[114:115], v[86:87], v[88:89]
	s_waitcnt lgkmcnt(13)
	v_mov_b32_e32 v156, v159
	v_pk_fma_f32 v[88:89], v[118:119], v[86:87], v[154:155] op_sel:[0,1,0] op_sel_hi:[1,0,1]
	v_mov_b32_e32 v157, v158
	ds_write2st64_b32 v190, v87, v86 offset0:16 offset1:17
	v_pk_fma_f32 v[86:87], v[114:115], v[86:87], v[88:89]
	s_waitcnt lgkmcnt(13)
	v_mov_b32_e32 v158, v161
	v_pk_fma_f32 v[88:89], v[118:119], v[86:87], v[156:157] op_sel:[0,1,0] op_sel_hi:[1,0,1]
	v_mov_b32_e32 v159, v160
	ds_write2st64_b32 v191, v87, v86 offset0:18 offset1:19
	v_pk_fma_f32 v[86:87], v[114:115], v[86:87], v[88:89]
	s_waitcnt lgkmcnt(13)
	v_mov_b32_e32 v160, v163
	v_pk_fma_f32 v[88:89], v[118:119], v[86:87], v[158:159] op_sel:[0,1,0] op_sel_hi:[1,0,1]
	v_mov_b32_e32 v161, v162
	ds_write2st64_b32 v192, v87, v86 offset0:20 offset1:21
	v_pk_fma_f32 v[86:87], v[114:115], v[86:87], v[88:89]
	s_waitcnt lgkmcnt(13)
	v_mov_b32_e32 v162, v165
	v_pk_fma_f32 v[88:89], v[118:119], v[86:87], v[160:161] op_sel:[0,1,0] op_sel_hi:[1,0,1]
	v_mov_b32_e32 v163, v164
	ds_write2st64_b32 v193, v87, v86 offset0:22 offset1:23
	v_pk_fma_f32 v[86:87], v[114:115], v[86:87], v[88:89]
	s_waitcnt lgkmcnt(13)
	v_mov_b32_e32 v164, v167
	v_pk_fma_f32 v[88:89], v[118:119], v[86:87], v[162:163] op_sel:[0,1,0] op_sel_hi:[1,0,1]
	v_mov_b32_e32 v165, v166
	ds_write2st64_b32 v194, v87, v86 offset0:24 offset1:25
	v_pk_fma_f32 v[86:87], v[114:115], v[86:87], v[88:89]
	s_waitcnt lgkmcnt(13)
	v_mov_b32_e32 v166, v169
	v_pk_fma_f32 v[88:89], v[118:119], v[86:87], v[164:165] op_sel:[0,1,0] op_sel_hi:[1,0,1]
	v_mov_b32_e32 v167, v168
	ds_write2st64_b32 v195, v87, v86 offset0:26 offset1:27
	v_pk_fma_f32 v[86:87], v[114:115], v[86:87], v[88:89]
	ds_write2st64_b32 v196, v87, v86 offset0:28 offset1:29
	v_pk_fma_f32 v[88:89], v[118:119], v[86:87], v[166:167] op_sel:[0,1,0] op_sel_hi:[1,0,1]
	v_mov_b64_e32 v[84:85], s[10:11]
	v_pk_fma_f32 v[120:121], v[114:115], v[86:87], v[88:89]
	ds_write2st64_b32 v197, v121, v120 offset0:30 offset1:31
	ds_read_b128 v[86:89], v126
	ds_read_b128 v[90:93], v126 offset:16
	ds_read_b128 v[132:135], v126 offset:128
	ds_read_b128 v[136:139], v126 offset:144
	ds_read_b128 v[140:143], v126 offset:256
	ds_read_b128 v[144:147], v126 offset:272
	ds_read_b128 v[148:151], v126 offset:384
	ds_read_b128 v[152:155], v126 offset:400
	ds_read2_b32 v[180:181], v128 offset1:16
	ds_read2_b32 v[182:183], v128 offset0:32 offset1:48
	v_add_u32_e32 v95, 0x400, v95
	ds_read_b128 v[198:201], v95
	ds_read_b128 v[202:205], v95 offset:16
	s_waitcnt lgkmcnt(11)
; #define LAS __attribute__((address_space(3)))
; __device__ __forceinline__ unsigned f2bf(float f) { unsigned u = __builtin_bit_cast(unsigned, f); return (u + 0x7fffu + ((u >> 16) & 1u)) >> 16; }
; __device__ __forceinline__ unsigned pk2(float lo, float hi) { const f32x2 v = {lo, hi}; return __builtin_bit_cast(unsigned, __builtin_convertvector(v, bf16x2_t)); }
; __device__ __forceinline__ float gelu_tanh(float x) { const float t = 1.5957691216057308f * (x + 0.044715f * x * x * x); return x * __builtin_amdgcn_rcpf(1.0f + __expf(-t)); }
; template <bool FULL>
; __device__ __forceinline__ void ssm_core(const Args& a, LAS unsigned char* wl, int j, int L, bool samp, int n, int g, int tb, int te, float& hr, float& hi, int lane) {
;     ...
;                 for (int kk = 0; kk < 4; ++kk) { const LAS f32x4* hp = (const LAS f32x4*)(BUs + c * SSM_BUS + 32 * kk + 8 * G4); const f32x4 h0 = hp[0], h1 = hp[1];
;                     hw[kk].x = pk2(h0[0], h0[1]); hw[kk].y = pk2(h0[2], h0[3]); hw[kk].z = pk2(h1[0], h1[1]); hw[kk].w = pk2(h1[2], h1[3]); }
; #pragma unroll
;                 for (int kk = 0; kk < 4; ++kk) y = mfma_t(__builtin_bit_cast(bf16x8, hw[kk]), Cf[kk], y);
; #pragma unroll
;                 for (int i = 0; i < 4; ++i) { const float us = Us[(16 * k + 4 * G4 + i) * 16 + c]; Y[(rowbase + t0 + 16 * k + 4 * G4 + i) * D + g * NQ + c] = (bf16_t)f2bf(gelu_tanh(y[i] + dsk * us)); }
	v_cvt_pk_bf16_f32 v86, v86, v87
	v_cvt_pk_bf16_f32 v87, v88, v89
	s_waitcnt lgkmcnt(10)
	v_cvt_pk_bf16_f32 v88, v90, v91
	v_cvt_pk_bf16_f32 v89, v92, v93
	v_mov_b64_e32 v[82:83], s[8:9]
	s_waitcnt lgkmcnt(9)
	v_cvt_pk_bf16_f32 v90, v132, v133
	v_cvt_pk_bf16_f32 v91, v134, v135
	s_waitcnt lgkmcnt(8)
	v_cvt_pk_bf16_f32 v92, v136, v137
	v_cvt_pk_bf16_f32 v93, v138, v139
	s_nop 4
	s_waitcnt lgkmcnt(7)
	v_cvt_pk_bf16_f32 v132, v140, v141
	v_mfma_f32_16x16x32_bf16 v[82:85], v[86:89], v[18:21], v[82:85]
	v_cvt_pk_bf16_f32 v133, v142, v143
	s_waitcnt lgkmcnt(6)
	v_cvt_pk_bf16_f32 v134, v144, v145
	v_cvt_pk_bf16_f32 v135, v146, v147
	s_nop 7
	s_waitcnt lgkmcnt(5)
	v_cvt_pk_bf16_f32 v136, v148, v149
	s_nop 4
	v_cvt_pk_bf16_f32 v137, v150, v151
	v_mfma_f32_16x16x32_bf16 v[82:85], v[90:93], v[22:25], v[82:85]
	s_waitcnt lgkmcnt(4)
	v_cvt_pk_bf16_f32 v138, v152, v153
	s_nop 7
	v_cvt_pk_bf16_f32 v139, v154, v155
	s_nop 4
	v_lshl_add_u64 v[174:175], v[116:117], 0, s[36:37]
	v_mfma_f32_16x16x32_bf16 v[82:85], v[132:135], v[26:29], v[82:85]
	s_nop 7
	v_add_co_u32_e32 v176, vcc, s41, v174
	s_nop 4
	s_add_u32 s36, s36, 0x10000
	v_mfma_f32_16x16x32_bf16 v[82:85], v[136:139], v[30:33], v[82:85]
	s_nop 7
	v_addc_co_u32_e32 v177, vcc, 0, v175, vcc
	v_add_co_u32_e32 v174, vcc, s42, v174
	s_waitcnt lgkmcnt(3)
	s_nop 2
	v_fma_f32 v82, v127, v180, v82
	v_fma_f32 v83, v127, v181, v83
	s_waitcnt lgkmcnt(2)
	v_fma_f32 v84, v127, v182, v84
	v_fmac_f32_e32 v85, v127, v183
	v_mul_f32_e32 v86, 0x3d372713, v82
	v_mul_f32_e32 v87, 0x3d372713, v83
	v_mul_f32_e32 v88, 0x3d372713, v84
	v_mul_f32_e32 v89, 0x3d372713, v85
	v_mul_f32_e32 v86, v82, v86
	v_mul_f32_e32 v87, v83, v87
	v_mul_f32_e32 v88, v84, v88
	v_mul_f32_e32 v89, v85, v89
	v_fma_f32 v86, v82, v86, v82
	v_fma_f32 v87, v83, v87, v83
	v_fma_f32 v88, v84, v88, v84
	v_fma_f32 v89, v85, v89, v85
	v_mul_f32_e32 v86, 0xbfcc422a, v86
	v_mul_f32_e32 v87, 0xbfcc422a, v87
	v_mul_f32_e32 v88, 0xbfcc422a, v88
	v_mul_f32_e32 v89, 0xbfcc422a, v89
	v_mul_f32_e32 v86, 0x3fb8aa3b, v86
	v_mul_f32_e32 v87, 0x3fb8aa3b, v87
	v_mul_f32_e32 v88, 0x3fb8aa3b, v88
	v_mul_f32_e32 v89, 0x3fb8aa3b, v89
	v_exp_f32_e32 v86, v86
	v_exp_f32_e32 v87, v87
	v_exp_f32_e32 v88, v88
	v_exp_f32_e32 v89, v89
	v_add_f32_e32 v86, 1.0, v86
	v_add_f32_e32 v87, 1.0, v87
	v_add_f32_e32 v88, 1.0, v88
	v_add_f32_e32 v89, 1.0, v89
	v_rcp_f32_e32 v86, v86
	v_rcp_f32_e32 v87, v87
	v_rcp_f32_e32 v88, v88
	v_rcp_f32_e32 v89, v89
	v_mul_f32_e32 v82, v82, v86
	v_mul_f32_e32 v83, v83, v87
	v_mul_f32_e32 v84, v84, v88
	v_mul_f32_e32 v85, v85, v89
	v_bfe_u32 v86, v82, 16, 1
	v_bfe_u32 v87, v83, 16, 1
	v_bfe_u32 v88, v84, 16, 1
	v_bfe_u32 v89, v85, 16, 1
	v_add3_u32 v82, v82, v86, s40
	v_addc_co_u32_e32 v175, vcc, 0, v175, vcc
	v_add3_u32 v83, v83, v87, s40
	v_add3_u32 v84, v84, v88, s40
	v_add3_u32 v85, v85, v89, s40
	global_store_short_d16_hi v[176:177], v82, off offset:-4096
	global_store_short_d16_hi v[176:177], v83, off
	global_store_short_d16_hi v[174:175], v84, off offset:-4096
	global_store_short_d16_hi v[174:175], v85, off
	s_addc_u32 s37, s37, 0
	s_cmp_eq_u32 s36, 0x40000
	v_add_u32_e32 v128, 0x400, v128
	s_cbranch_scc0 .LBB0_286
	v_lshl_add_u64 v[116:117], v[116:117], 0, s[16:17]
	s_and_b64 vcc, exec, s[34:35]
	s_cbranch_vccnz .LBB0_281
	s_mov_b32 s36, s43
	s_branch .LBB0_283
